# pre_phase (instruction-bound): pre_item decode hoisted out of the tile loop (per-phase table, per-pass select) and reused on the compute side
# speedup vs baseline: 1.0041x; 1.0041x over previous
.LBB0_881:
	s_and_b64 vcc, exec, s[24:25]
	s_mov_b32 s52, 0x20000
	s_mov_b32 s53, 0x22000
	s_mov_b32 s56, 0x26000
	s_cbranch_vccz .LBB0_1039
	v_readlane_b32 s12, v254, 35
	s_cmp_gt_i32 s12, 5
	s_mov_b64 s[24:25], -1
	s_cbranch_scc0 .LBB0_1059
	v_readlane_b32 s12, v254, 35
	s_cmp_gt_i32 s12, 6
	s_cbranch_scc0 .LBB0_1041
	v_readlane_b32 s12, v254, 29
	s_cmpk_gt_i32 s12, 0x87f
	s_mov_b32 s37, 0x7fffffc0
	v_mbcnt_lo_u32_b32 v0, -1, 0
	v_mbcnt_hi_u32_b32 v0, -1, v0
	s_cbranch_scc1 .LBB0_1040
	s_load_dwordx2 s[12:13], s[0:1], 0x60
	s_load_dwordx2 s[24:25], s[0:1], 0x90
	s_mul_i32 s27, s62, 0x2c00
	s_mul_hi_i32 s26, s62, 0x2c00
	v_readlane_b32 s28, v254, 30
	s_waitcnt lgkmcnt(0)
	s_add_u32 s50, s12, s27
	s_addc_u32 s51, s13, s26
	s_add_u32 s52, s50, 0x1600
	s_mul_i32 s12, s62, 0x180
	s_addc_u32 s53, s51, 0
	s_ashr_i32 s13, s12, 31
	s_waitcnt vmcnt(0)
	v_ashrrev_i32_e32 v2, 3, v0
	v_lshl_add_u32 v45, s28, 6, v0
	s_lshl_b64 s[12:13], s[12:13], 2
	v_lshl_add_u32 v47, s28, 3, v2
	v_lshlrev_b32_e32 v2, 3, v0
	v_and_b32_e32 v0, 7, v0
	s_add_u32 s54, s24, s12
	s_movk_i32 s12, 0x60
	v_and_b32_e32 v2, 56, v2
	v_lshl_add_u32 v0, v0, 5, 0
	s_addc_u32 s55, s25, s13
	v_bfe_u32 v46, v45, 3, 4
	v_cmp_gt_i32_e64 s[42:43], s12, v47
	v_lshl_or_b32 v48, v47, 6, v2
	v_lshl_add_u32 v49, v47, 8, v0
	v_readlane_b32 s12, v254, 29
	s_mov_b32 s98, 0x5555556
	v_mov_b32_e32 v122, v45
	v_min_i32_e32 v122, 0xaff, v122
	v_mov_b32_e32 v123, 0
	v_cmp_lt_u32_e32 vcc, 0x2ff, v122
	v_addc_co_u32_e32 v123, vcc, 0, v123, vcc
	v_cmp_lt_u32_e32 vcc, 0x5ff, v122
	v_addc_co_u32_e32 v123, vcc, 0, v123, vcc
	v_mul_u32_u24_e32 v124, 0x300, v123
	v_sub_u32_e32 v124, v122, v124
	v_mul_hi_u32 v125, v124, s98
	v_mul_u32_u24_e32 v126, 48, v125
	v_sub_u32_e32 v126, v124, v126
	v_mul_u32_u24_e32 v127, 0x180, v123
	v_lshl_add_u32 v127, v126, 3, v127
	v_subrev_u32_e32 v128, 0x900, v122
	v_bfe_u32 v129, v128, 3, 4
	v_lshrrev_b32_e32 v130, 7, v128
	v_and_b32_e32 v131, 7, v128
	v_lshlrev_b32_e32 v131, 3, v131
	v_lshl_add_u32 v131, v130, 6, v131
	v_add_u32_e32 v131, 0x480, v131
	v_subrev_u32_e32 v132, 0xa00, v122
	v_lshrrev_b32_e32 v133, 4, v132
	v_and_b32_e32 v134, 15, v132
	v_lshlrev_b32_e32 v134, 3, v134
	v_add_u32_e32 v134, 0x500, v134
	v_cmp_lt_u32_e32 vcc, 0x9ff, v122
	v_cndmask_b32_e32 v110, v131, v134, vcc
	v_cndmask_b32_e32 v111, v129, v133, vcc
	v_cmp_lt_u32_e32 vcc, 0x8ff, v122
	v_cndmask_b32_e32 v110, v127, v110, vcc
	v_cndmask_b32_e32 v111, v125, v111, vcc
	v_add_u32_e32 v122, 0x200, v45
	v_min_i32_e32 v122, 0xaff, v122
	v_mov_b32_e32 v123, 0
	v_cmp_lt_u32_e32 vcc, 0x2ff, v122
	v_addc_co_u32_e32 v123, vcc, 0, v123, vcc
	v_cmp_lt_u32_e32 vcc, 0x5ff, v122
	v_addc_co_u32_e32 v123, vcc, 0, v123, vcc
	v_mul_u32_u24_e32 v124, 0x300, v123
	v_sub_u32_e32 v124, v122, v124
	v_mul_hi_u32 v125, v124, s98
	v_mul_u32_u24_e32 v126, 48, v125
	v_sub_u32_e32 v126, v124, v126
	v_mul_u32_u24_e32 v127, 0x180, v123
	v_lshl_add_u32 v127, v126, 3, v127
	v_subrev_u32_e32 v128, 0x900, v122
	v_bfe_u32 v129, v128, 3, 4
	v_lshrrev_b32_e32 v130, 7, v128
	v_and_b32_e32 v131, 7, v128
	v_lshlrev_b32_e32 v131, 3, v131
	v_lshl_add_u32 v131, v130, 6, v131
	v_add_u32_e32 v131, 0x480, v131
	v_subrev_u32_e32 v132, 0xa00, v122
	v_lshrrev_b32_e32 v133, 4, v132
	v_and_b32_e32 v134, 15, v132
	v_lshlrev_b32_e32 v134, 3, v134
	v_add_u32_e32 v134, 0x500, v134
	v_cmp_lt_u32_e32 vcc, 0x9ff, v122
	v_cndmask_b32_e32 v112, v131, v134, vcc
	v_cndmask_b32_e32 v113, v129, v133, vcc
	v_cmp_lt_u32_e32 vcc, 0x8ff, v122
	v_cndmask_b32_e32 v112, v127, v112, vcc
	v_cndmask_b32_e32 v113, v125, v113, vcc
	v_add_u32_e32 v122, 0x400, v45
	v_min_i32_e32 v122, 0xaff, v122
	v_mov_b32_e32 v123, 0
	v_cmp_lt_u32_e32 vcc, 0x2ff, v122
	v_addc_co_u32_e32 v123, vcc, 0, v123, vcc
	v_cmp_lt_u32_e32 vcc, 0x5ff, v122
	v_addc_co_u32_e32 v123, vcc, 0, v123, vcc
	v_mul_u32_u24_e32 v124, 0x300, v123
	v_sub_u32_e32 v124, v122, v124
	v_mul_hi_u32 v125, v124, s98
	v_mul_u32_u24_e32 v126, 48, v125
	v_sub_u32_e32 v126, v124, v126
	v_mul_u32_u24_e32 v127, 0x180, v123
	v_lshl_add_u32 v127, v126, 3, v127
	v_subrev_u32_e32 v128, 0x900, v122
	v_bfe_u32 v129, v128, 3, 4
	v_lshrrev_b32_e32 v130, 7, v128
	v_and_b32_e32 v131, 7, v128
	v_lshlrev_b32_e32 v131, 3, v131
	v_lshl_add_u32 v131, v130, 6, v131
	v_add_u32_e32 v131, 0x480, v131
	v_subrev_u32_e32 v132, 0xa00, v122
	v_lshrrev_b32_e32 v133, 4, v132
	v_and_b32_e32 v134, 15, v132
	v_lshlrev_b32_e32 v134, 3, v134
	v_add_u32_e32 v134, 0x500, v134
	v_cmp_lt_u32_e32 vcc, 0x9ff, v122
	v_cndmask_b32_e32 v114, v131, v134, vcc
	v_cndmask_b32_e32 v115, v129, v133, vcc
	v_cmp_lt_u32_e32 vcc, 0x8ff, v122
	v_cndmask_b32_e32 v114, v127, v114, vcc
	v_cndmask_b32_e32 v115, v125, v115, vcc
	v_add_u32_e32 v122, 0x600, v45
	v_min_i32_e32 v122, 0xaff, v122
	v_mov_b32_e32 v123, 0
	v_cmp_lt_u32_e32 vcc, 0x2ff, v122
	v_addc_co_u32_e32 v123, vcc, 0, v123, vcc
	v_cmp_lt_u32_e32 vcc, 0x5ff, v122
	v_addc_co_u32_e32 v123, vcc, 0, v123, vcc
	v_mul_u32_u24_e32 v124, 0x300, v123
	v_sub_u32_e32 v124, v122, v124
	v_mul_hi_u32 v125, v124, s98
	v_mul_u32_u24_e32 v126, 48, v125
	v_sub_u32_e32 v126, v124, v126
	v_mul_u32_u24_e32 v127, 0x180, v123
	v_lshl_add_u32 v127, v126, 3, v127
	v_subrev_u32_e32 v128, 0x900, v122
	v_bfe_u32 v129, v128, 3, 4
	v_lshrrev_b32_e32 v130, 7, v128
	v_and_b32_e32 v131, 7, v128
	v_lshlrev_b32_e32 v131, 3, v131
	v_lshl_add_u32 v131, v130, 6, v131
	v_add_u32_e32 v131, 0x480, v131
	v_subrev_u32_e32 v132, 0xa00, v122
	v_lshrrev_b32_e32 v133, 4, v132
	v_and_b32_e32 v134, 15, v132
	v_lshlrev_b32_e32 v134, 3, v134
	v_add_u32_e32 v134, 0x500, v134
	v_cmp_lt_u32_e32 vcc, 0x9ff, v122
	v_cndmask_b32_e32 v116, v131, v134, vcc
	v_cndmask_b32_e32 v117, v129, v133, vcc
	v_cmp_lt_u32_e32 vcc, 0x8ff, v122
	v_cndmask_b32_e32 v116, v127, v116, vcc
	v_cndmask_b32_e32 v117, v125, v117, vcc
	v_add_u32_e32 v122, 0x800, v45
	v_min_i32_e32 v122, 0xaff, v122
	v_mov_b32_e32 v123, 0
	v_cmp_lt_u32_e32 vcc, 0x2ff, v122
	v_addc_co_u32_e32 v123, vcc, 0, v123, vcc
	v_cmp_lt_u32_e32 vcc, 0x5ff, v122
	v_addc_co_u32_e32 v123, vcc, 0, v123, vcc
	v_mul_u32_u24_e32 v124, 0x300, v123
	v_sub_u32_e32 v124, v122, v124
	v_mul_hi_u32 v125, v124, s98
	v_mul_u32_u24_e32 v126, 48, v125
	v_sub_u32_e32 v126, v124, v126
	v_mul_u32_u24_e32 v127, 0x180, v123
	v_lshl_add_u32 v127, v126, 3, v127
	v_subrev_u32_e32 v128, 0x900, v122
	v_bfe_u32 v129, v128, 3, 4
	v_lshrrev_b32_e32 v130, 7, v128
	v_and_b32_e32 v131, 7, v128
	v_lshlrev_b32_e32 v131, 3, v131
	v_lshl_add_u32 v131, v130, 6, v131
	v_add_u32_e32 v131, 0x480, v131
	v_subrev_u32_e32 v132, 0xa00, v122
	v_lshrrev_b32_e32 v133, 4, v132
	v_and_b32_e32 v134, 15, v132
	v_lshlrev_b32_e32 v134, 3, v134
	v_add_u32_e32 v134, 0x500, v134
	v_cmp_lt_u32_e32 vcc, 0x9ff, v122
	v_cndmask_b32_e32 v118, v131, v134, vcc
	v_cndmask_b32_e32 v119, v129, v133, vcc
	v_cmp_lt_u32_e32 vcc, 0x8ff, v122
	v_cndmask_b32_e32 v118, v127, v118, vcc
	v_cndmask_b32_e32 v119, v125, v119, vcc
	v_add_u32_e32 v122, 0xa00, v45
	v_min_i32_e32 v122, 0xaff, v122
	v_mov_b32_e32 v123, 0
	v_cmp_lt_u32_e32 vcc, 0x2ff, v122
	v_addc_co_u32_e32 v123, vcc, 0, v123, vcc
	v_cmp_lt_u32_e32 vcc, 0x5ff, v122
	v_addc_co_u32_e32 v123, vcc, 0, v123, vcc
	v_mul_u32_u24_e32 v124, 0x300, v123
	v_sub_u32_e32 v124, v122, v124
	v_mul_hi_u32 v125, v124, s98
	v_mul_u32_u24_e32 v126, 48, v125
	v_sub_u32_e32 v126, v124, v126
	v_mul_u32_u24_e32 v127, 0x180, v123
	v_lshl_add_u32 v127, v126, 3, v127
	v_subrev_u32_e32 v128, 0x900, v122
	v_bfe_u32 v129, v128, 3, 4
	v_lshrrev_b32_e32 v130, 7, v128
	v_and_b32_e32 v131, 7, v128
	v_lshlrev_b32_e32 v131, 3, v131
	v_lshl_add_u32 v131, v130, 6, v131
	v_add_u32_e32 v131, 0x480, v131
	v_subrev_u32_e32 v132, 0xa00, v122
	v_lshrrev_b32_e32 v133, 4, v132
	v_and_b32_e32 v134, 15, v132
	v_lshlrev_b32_e32 v134, 3, v134
	v_add_u32_e32 v134, 0x500, v134
	v_cmp_lt_u32_e32 vcc, 0x9ff, v122
	v_cndmask_b32_e32 v120, v131, v134, vcc
	v_cndmask_b32_e32 v121, v129, v133, vcc
	v_cmp_lt_u32_e32 vcc, 0x8ff, v122
	v_cndmask_b32_e32 v120, v127, v120, vcc
	v_cndmask_b32_e32 v121, v125, v121, vcc
	s_branch .LBB0_887

.LBB0_889:
	v_add_u32_e32 v0, s24, v45
	s_waitcnt vmcnt(2)
	s_cmp_eq_u32 s24, 0
	s_cbranch_scc0 .Lpre_sel1
	v_mov_b32_e32 v104, v110
	v_mov_b32_e32 v105, v111
	v_mov_b32_e32 v106, v112
	v_mov_b32_e32 v107, v113
	v_mov_b32_e32 v108, v114
	v_mov_b32_e32 v109, v115
	s_branch .Lpre_seld
.Lpre_sel1:
	v_mov_b32_e32 v104, v116
	v_mov_b32_e32 v105, v117
	v_mov_b32_e32 v106, v118
	v_mov_b32_e32 v107, v119
	v_mov_b32_e32 v108, v120
	v_mov_b32_e32 v109, v121
.Lpre_seld:
	v_mov_b32_e32 v2, v104
	v_mov_b32_e32 v3, v105
	v_add_u32_e32 v4, s13, v3
	v_cmp_lt_i32_e64 s[44:45], s91, v4
	s_and_saveexec_b64 s[24:25], s[44:45]
	s_xor_b64 s[24:25], exec, s[24:25]
	s_cbranch_execz .LBB0_899
	v_add_u32_e32 v3, 0xffffff00, v4
	v_lshlrev_b32_e32 v5, 6, v4
	s_waitcnt vmcnt(1)
	v_lshrrev_b32_e32 v6, 6, v3
	v_and_or_b32 v5, v5, s96, v6
	v_cndmask_b32_e64 v3, v5, v3, s[40:41]
	v_add_u32_e32 v3, s34, v3
.LBB0_899:
	s_andn2_saveexec_b64 s[24:25], s[24:25]
	v_add_u32_e32 v3, s35, v4
	s_or_b64 exec, exec, s[24:25]
	s_waitcnt vmcnt(1)
	v_mov_b64_e32 v[6:7], s[16:17]
	v_mad_i64_i32 v[6:7], s[24:25], v3, s69, v[6:7]
	v_ashrrev_i32_e32 v3, 31, v2
	v_lshl_add_u64 v[6:7], v[2:3], 1, v[6:7]
	global_load_dwordx4 v[26:29], v[6:7], off offset:1536
	v_cmp_lt_i32_e64 s[44:45], s30, v4
	s_nop 1
	v_subbrev_co_u32_e64 v5, s[44:45], 0, v4, s[44:45]
	v_cmp_lt_i32_e64 s[44:45], s91, v5
	s_and_saveexec_b64 s[24:25], s[44:45]
	s_xor_b64 s[24:25], exec, s[24:25]
	v_add_u32_e32 v6, 0xffffff00, v5
	v_lshlrev_b32_e32 v5, 6, v5
	v_lshrrev_b32_e32 v7, 6, v6
	v_and_or_b32 v5, v5, s96, v7
	v_cndmask_b32_e64 v5, v5, v6, s[40:41]
	v_add_u32_e32 v6, s34, v5
	s_andn2_saveexec_b64 s[24:25], s[24:25]
	v_add_u32_e32 v6, s35, v5
	s_or_b64 exec, exec, s[24:25]
	v_mov_b64_e32 v[8:9], s[16:17]
	v_mad_i64_i32 v[6:7], s[24:25], v6, s69, v[8:9]
	v_lshl_add_u64 v[6:7], v[2:3], 1, v[6:7]
	global_load_dwordx4 v[30:33], v[6:7], off offset:1536
	v_add_u32_e32 v5, 1, v4
	v_cmp_gt_i32_e64 s[44:45], s31, v5
	s_nop 1
	v_cndmask_b32_e64 v5, v4, v5, s[44:45]
	v_cmp_lt_i32_e64 s[44:45], s91, v5
	s_and_saveexec_b64 s[24:25], s[44:45]
	s_xor_b64 s[24:25], exec, s[24:25]
	v_add_u32_e32 v4, 0xffffff00, v5
	v_lshlrev_b32_e32 v5, 6, v5
	v_lshrrev_b32_e32 v6, 6, v4
	v_and_or_b32 v5, v5, s96, v6
	v_cndmask_b32_e64 v4, v5, v4, s[40:41]
	v_add_u32_e32 v4, s34, v4
	s_andn2_saveexec_b64 s[24:25], s[24:25]
	v_add_u32_e32 v4, s35, v5
	s_or_b64 exec, exec, s[24:25]
	v_mov_b64_e32 v[6:7], s[16:17]
	v_mad_i64_i32 v[4:5], s[24:25], v4, s69, v[6:7]
	v_lshl_add_u64 v[2:3], v[2:3], 1, v[4:5]
	global_load_dwordx4 v[34:37], v[2:3], off offset:1536
	v_add_u32_e32 v51, 0x200, v0
	v_mov_b32_e32 v2, v106
	v_mov_b32_e32 v3, v107
	v_add_u32_e32 v4, s13, v3
	v_cmp_lt_i32_e64 s[44:45], s91, v4
	s_and_saveexec_b64 s[24:25], s[44:45]
	s_xor_b64 s[24:25], exec, s[24:25]
	v_add_u32_e32 v3, 0xffffff00, v4
	v_lshlrev_b32_e32 v5, 6, v4
	v_lshrrev_b32_e32 v6, 6, v3
	v_and_or_b32 v5, v5, s96, v6
	v_cndmask_b32_e64 v3, v5, v3, s[40:41]
	v_add_u32_e32 v3, s34, v3
	s_andn2_saveexec_b64 s[24:25], s[24:25]
	v_add_u32_e32 v3, s35, v4
	s_or_b64 exec, exec, s[24:25]
	v_mov_b64_e32 v[6:7], s[16:17]
	v_mad_i64_i32 v[6:7], s[24:25], v3, s69, v[6:7]
	v_ashrrev_i32_e32 v3, 31, v2
	v_lshl_add_u64 v[6:7], v[2:3], 1, v[6:7]
	global_load_dwordx4 v[14:17], v[6:7], off offset:1536
	v_cmp_lt_i32_e64 s[44:45], s30, v4
	s_nop 1
	v_subbrev_co_u32_e64 v5, s[44:45], 0, v4, s[44:45]
	v_cmp_lt_i32_e64 s[44:45], s91, v5
	s_and_saveexec_b64 s[24:25], s[44:45]
	s_xor_b64 s[24:25], exec, s[24:25]
	v_add_u32_e32 v6, 0xffffff00, v5
	v_lshlrev_b32_e32 v5, 6, v5
	v_lshrrev_b32_e32 v7, 6, v6
	v_and_or_b32 v5, v5, s96, v7
	v_cndmask_b32_e64 v5, v5, v6, s[40:41]
	v_add_u32_e32 v6, s34, v5
	s_andn2_saveexec_b64 s[24:25], s[24:25]
	v_add_u32_e32 v6, s35, v5
	s_or_b64 exec, exec, s[24:25]
	v_mov_b64_e32 v[8:9], s[16:17]
	v_mad_i64_i32 v[6:7], s[24:25], v6, s69, v[8:9]
	v_lshl_add_u64 v[6:7], v[2:3], 1, v[6:7]
	global_load_dwordx4 v[18:21], v[6:7], off offset:1536
	v_add_u32_e32 v5, 1, v4
	v_cmp_gt_i32_e64 s[44:45], s31, v5
	s_nop 1
	v_cndmask_b32_e64 v5, v4, v5, s[44:45]
	v_cmp_lt_i32_e64 s[44:45], s91, v5
	s_and_saveexec_b64 s[24:25], s[44:45]
	s_xor_b64 s[24:25], exec, s[24:25]
	v_add_u32_e32 v4, 0xffffff00, v5
	v_lshlrev_b32_e32 v5, 6, v5
	v_lshrrev_b32_e32 v6, 6, v4
	v_and_or_b32 v5, v5, s96, v6
	v_cndmask_b32_e64 v4, v5, v4, s[40:41]
	v_add_u32_e32 v4, s34, v4
	s_andn2_saveexec_b64 s[24:25], s[24:25]
	v_add_u32_e32 v4, s35, v5
	s_or_b64 exec, exec, s[24:25]
	v_mov_b64_e32 v[6:7], s[16:17]
	v_mad_i64_i32 v[4:5], s[24:25], v4, s69, v[6:7]
	v_lshl_add_u64 v[2:3], v[2:3], 1, v[4:5]
	global_load_dwordx4 v[22:25], v[2:3], off offset:1536
	v_add_u32_e32 v50, 0x400, v0
	s_waitcnt vmcnt(6)
	v_mov_b32_e32 v10, v108
	v_mov_b32_e32 v2, v109
	v_add_u32_e32 v12, s13, v2
	v_cmp_lt_i32_e64 s[48:49], s91, v12
	s_and_saveexec_b64 s[24:25], s[48:49]
	s_xor_b64 s[24:25], exec, s[24:25]
	v_add_u32_e32 v2, 0xffffff00, v12
	v_lshlrev_b32_e32 v3, 6, v12
	v_lshrrev_b32_e32 v4, 6, v2
	v_and_or_b32 v3, v3, s96, v4
	v_cndmask_b32_e64 v2, v3, v2, s[40:41]
	v_add_u32_e32 v2, s34, v2
	s_andn2_saveexec_b64 s[24:25], s[24:25]
	v_add_u32_e32 v2, s35, v12
	s_or_b64 exec, exec, s[24:25]
	v_mov_b64_e32 v[4:5], s[16:17]
	v_mad_i64_i32 v[2:3], s[24:25], v2, s69, v[4:5]
	v_ashrrev_i32_e32 v11, 31, v10
	v_lshl_add_u64 v[2:3], v[10:11], 1, v[2:3]
	global_load_dwordx4 v[2:5], v[2:3], off offset:1536
	v_cmp_lt_i32_e64 s[48:49], s30, v12
	s_nop 1
	v_subbrev_co_u32_e64 v6, s[48:49], 0, v12, s[48:49]
	v_cmp_lt_i32_e64 s[48:49], s91, v6
	s_and_saveexec_b64 s[24:25], s[48:49]
	s_xor_b64 s[24:25], exec, s[24:25]
	v_add_u32_e32 v7, 0xffffff00, v6
	v_lshlrev_b32_e32 v6, 6, v6
	v_lshrrev_b32_e32 v8, 6, v7
	v_and_or_b32 v6, v6, s96, v8
	v_cndmask_b32_e64 v6, v6, v7, s[40:41]
	v_add_u32_e32 v7, s34, v6
	s_andn2_saveexec_b64 s[24:25], s[24:25]
	v_add_u32_e32 v7, s35, v6
	s_or_b64 exec, exec, s[24:25]
	v_mov_b64_e32 v[8:9], s[16:17]
	v_mad_i64_i32 v[6:7], s[24:25], v7, s69, v[8:9]
	v_lshl_add_u64 v[6:7], v[10:11], 1, v[6:7]
	global_load_dwordx4 v[6:9], v[6:7], off offset:1536
	v_add_u32_e32 v13, 1, v12
	v_cmp_gt_i32_e64 s[48:49], s31, v13
	s_nop 1
	v_cndmask_b32_e64 v13, v12, v13, s[48:49]
	v_cmp_lt_i32_e64 s[48:49], s91, v13
	s_and_saveexec_b64 s[24:25], s[48:49]
	s_xor_b64 s[24:25], exec, s[24:25]
	v_add_u32_e32 v12, 0xffffff00, v13
	v_lshlrev_b32_e32 v13, 6, v13
	v_lshrrev_b32_e32 v38, 6, v12
	v_and_or_b32 v13, v13, s96, v38
	v_cndmask_b32_e64 v12, v13, v12, s[40:41]
	v_add_u32_e32 v12, s34, v12
	s_andn2_saveexec_b64 s[24:25], s[24:25]
	v_add_u32_e32 v12, s35, v13
	s_or_b64 exec, exec, s[24:25]
	v_mov_b64_e32 v[38:39], s[16:17]
	v_mad_i64_i32 v[12:13], s[24:25], v12, s69, v[38:39]
	v_lshl_add_u64 v[10:11], v[10:11], 1, v[12:13]
	global_load_dwordx4 v[10:13], v[10:11], off offset:1536
	v_cmp_gt_i32_e64 s[48:49], s39, v0
	s_and_saveexec_b64 s[24:25], s[48:49]
	s_cbranch_execz .LBB0_978
	v_mov_b32_e32 v38, v104
	v_mov_b32_e32 v52, v105
	v_ashrrev_i32_e32 v39, 31, v38
	v_lshlrev_b64 v[40:41], 2, v[38:39]
	v_lshl_add_u64 v[58:59], s[50:51], 0, v[40:41]
	global_load_dwordx4 v[54:57], v[58:59], off offset:16
	s_nop 0
	global_load_dwordx4 v[58:61], v[58:59], off
	v_lshl_add_u64 v[98:99], s[52:53], 0, v[40:41]
	global_load_dwordx4 v[74:77], v[98:99], off offset:16
	global_load_dwordx4 v[78:81], v[98:99], off
	v_add_u32_e32 v42, s13, v52
	v_cmp_lt_i32_e32 vcc, s30, v42
	s_waitcnt vmcnt(12)
	v_lshlrev_b32_e32 v70, 16, v26
	v_and_b32_e32 v71, 0xffff0000, v26
	v_cndmask_b32_e64 v44, 0, 1.0, vcc
	s_waitcnt vmcnt(11)
	v_lshlrev_b32_e32 v62, 16, v30
	v_and_b32_e32 v63, 0xffff0000, v30
	v_lshl_add_u64 v[40:41], s[52:53], 0, v[40:41]
	v_pk_fma_f32 v[62:63], v[44:45], v[62:63], v[70:71] op_sel_hi:[0,1,1] neg_lo:[0,0,1] neg_hi:[0,0,1]
	v_cmp_gt_i32_e32 vcc, s36, v42
	v_lshlrev_b32_e32 v26, 16, v27
	v_and_b32_e32 v27, 0xffff0000, v27
	v_lshlrev_b32_e32 v30, 16, v31
	v_and_b32_e32 v31, 0xffff0000, v31
	v_cndmask_b32_e64 v0, 0, 1.0, vcc
	s_waitcnt vmcnt(10)
	v_lshlrev_b32_e32 v72, 16, v34
	v_and_b32_e32 v73, 0xffff0000, v34
	v_lshlrev_b32_e32 v34, 16, v35
	v_and_b32_e32 v35, 0xffff0000, v35
	v_pk_fma_f32 v[30:31], v[44:45], v[30:31], v[26:27] op_sel_hi:[0,1,1] neg_lo:[0,0,1] neg_hi:[0,0,1]
	v_ashrrev_i32_e32 v43, 31, v42
	s_movk_i32 s26, 0x17f
	v_cmp_lt_i32_e32 vcc, s26, v38
	s_waitcnt vmcnt(2)
	v_pk_fma_f32 v[58:59], v[58:59], v[62:63], v[70:71]
	v_pk_fma_f32 v[30:31], v[30:31], v[60:61], v[26:27]
	v_pk_fma_f32 v[26:27], v[0:1], v[34:35], v[26:27] op_sel_hi:[0,1,1] neg_lo:[0,0,1] neg_hi:[0,0,1]
	v_pk_fma_f32 v[40:41], v[0:1], v[72:73], v[70:71] op_sel_hi:[0,1,1] neg_lo:[0,0,1] neg_hi:[0,0,1]
	s_waitcnt vmcnt(0)
	v_pk_fma_f32 v[34:35], v[26:27], v[80:81], v[30:31]
	v_lshlrev_b32_e32 v26, 16, v28
	v_and_b32_e32 v27, 0xffff0000, v28
	v_lshlrev_b32_e32 v30, 16, v32
	v_and_b32_e32 v31, 0xffff0000, v32
	v_pk_fma_f32 v[40:41], v[78:79], v[40:41], v[58:59]
	v_lshlrev_b32_e32 v58, 16, v36
	v_and_b32_e32 v59, 0xffff0000, v36
	v_pk_fma_f32 v[30:31], v[44:45], v[30:31], v[26:27] op_sel_hi:[0,1,1] neg_lo:[0,0,1] neg_hi:[0,0,1]
	v_pk_fma_f32 v[30:31], v[30:31], v[54:55], v[26:27]
	v_pk_fma_f32 v[26:27], v[0:1], v[58:59], v[26:27] op_sel_hi:[0,1,1] neg_lo:[0,0,1] neg_hi:[0,0,1]
	v_pk_fma_f32 v[30:31], v[26:27], v[74:75], v[30:31]
	v_lshlrev_b32_e32 v26, 16, v29
	v_and_b32_e32 v27, 0xffff0000, v29
	v_lshlrev_b32_e32 v28, 16, v33
	v_and_b32_e32 v29, 0xffff0000, v33
	v_lshlrev_b32_e32 v32, 16, v37
	v_and_b32_e32 v33, 0xffff0000, v37
	v_pk_fma_f32 v[28:29], v[44:45], v[28:29], v[26:27] op_sel_hi:[0,1,1] neg_lo:[0,0,1] neg_hi:[0,0,1]
	v_pk_fma_f32 v[28:29], v[28:29], v[56:57], v[26:27]
	v_pk_fma_f32 v[26:27], v[0:1], v[32:33], v[26:27] op_sel_hi:[0,1,1] neg_lo:[0,0,1] neg_hi:[0,0,1]
	v_pk_fma_f32 v[28:29], v[26:27], v[76:77], v[28:29]
	v_lshl_add_u64 v[26:27], s[56:57], 0, v[42:43]
	s_and_saveexec_b64 s[26:27], vcc
	s_xor_b64 s[48:49], exec, s[26:27]
	s_cbranch_execz .LBB0_976
	v_cmp_lt_u32_e32 vcc, s88, v38
	s_and_saveexec_b64 s[26:27], vcc
	s_xor_b64 s[60:61], exec, s[26:27]
	s_cbranch_execz .LBB0_973
	s_movk_i32 s26, 0x47f
	v_cmp_lt_u32_e32 vcc, s26, v38
	s_and_saveexec_b64 s[26:27], vcc
	s_xor_b64 s[62:63], exec, s[26:27]
	s_cbranch_execz .LBB0_970
	s_movk_i32 s26, 0x4bf
	v_cmp_lt_u32_e32 vcc, s26, v38
	s_and_saveexec_b64 s[26:27], vcc
	s_xor_b64 s[26:27], exec, s[26:27]
	s_cbranch_execz .LBB0_967
	s_movk_i32 s28, 0x4ff
	v_cmp_lt_u32_e32 vcc, s28, v38
	s_and_saveexec_b64 s[28:29], vcc
	s_xor_b64 s[64:65], exec, s[28:29]
	s_cbranch_execz .LBB0_964
	v_mul_f32_e32 v30, 0xbfb8aa3b, v30
	v_mul_f32_e32 v31, 0xbfb8aa3b, v31
	v_mul_f32_e32 v28, 0xbfb8aa3b, v28
	v_mul_f32_e32 v0, 0xbfb8aa3b, v40
	v_mul_f32_e32 v32, 0xbfb8aa3b, v41
	v_mul_f32_e32 v33, 0xbfb8aa3b, v34
	v_mul_f32_e32 v34, 0xbfb8aa3b, v35
	v_exp_f32_e32 v30, v30
	v_exp_f32_e32 v31, v31
	v_exp_f32_e32 v28, v28
	v_mul_f32_e32 v29, 0xbfb8aa3b, v29
	v_exp_f32_e32 v0, v0
	v_exp_f32_e32 v32, v32
	v_exp_f32_e32 v33, v33
	v_exp_f32_e32 v34, v34
	v_exp_f32_e32 v29, v29
	v_add_f32_e32 v30, 1.0, v30
	v_add_f32_e32 v31, 1.0, v31
	v_add_f32_e32 v28, 1.0, v28
	v_lshlrev_b64 v[26:27], 9, v[26:27]
	v_add_f32_e32 v0, 1.0, v0
	v_add_f32_e32 v32, 1.0, v32
	v_add_f32_e32 v33, 1.0, v33
	v_add_f32_e32 v34, 1.0, v34
	v_rcp_f32_e32 v30, v30
	v_rcp_f32_e32 v31, v31
	v_rcp_f32_e32 v35, v28
	v_add_f32_e32 v28, 1.0, v29
	v_lshl_add_u64 v[26:27], s[14:15], 0, v[26:27]
	v_rcp_f32_e32 v0, v0
	v_rcp_f32_e32 v32, v32
	v_rcp_f32_e32 v33, v33
	v_rcp_f32_e32 v34, v34
	v_rcp_f32_e32 v36, v28
	v_cvt_pk_bf16_f32 v28, v0, v32
	v_cvt_pk_bf16_f32 v29, v33, v34
	v_cvt_pk_bf16_f32 v30, v30, v31
	v_cvt_pk_bf16_f32 v31, v35, v36
	v_lshl_add_u64 v[26:27], v[38:39], 1, v[26:27]
	global_store_dwordx4 v[26:27], v[28:31], off offset:-2304

.LBB0_978:
	s_or_b64 exec, exec, s[24:25]
	s_xor_b64 s[48:49], s[58:59], -1
	v_cmp_gt_i32_e32 vcc, s39, v51
	s_and_saveexec_b64 s[24:25], vcc
	s_cbranch_execz .LBB0_1007
	s_waitcnt vmcnt(7)
	v_mov_b32_e32 v26, v106
	v_mov_b32_e32 v33, v107
	s_waitcnt vmcnt(8)
	v_ashrrev_i32_e32 v27, 31, v26
	v_lshlrev_b64 v[28:29], 2, v[26:27]
	v_lshl_add_u64 v[38:39], s[50:51], 0, v[28:29]
	global_load_dwordx4 v[34:37], v[38:39], off offset:16
	s_nop 0
	global_load_dwordx4 v[38:41], v[38:39], off
	v_lshl_add_u64 v[100:101], s[52:53], 0, v[28:29]
	global_load_dwordx4 v[82:85], v[100:101], off offset:16
	global_load_dwordx4 v[86:89], v[100:101], off
	s_waitcnt vmcnt(11)
	v_add_u32_e32 v30, s13, v33
	v_cmp_lt_i32_e32 vcc, s30, v30
	s_waitcnt vmcnt(9)
	v_lshlrev_b32_e32 v42, 16, v14
	v_and_b32_e32 v43, 0xffff0000, v14
	v_cndmask_b32_e64 v32, 0, 1.0, vcc
	s_waitcnt vmcnt(8)
	v_lshlrev_b32_e32 v52, 16, v18
	v_and_b32_e32 v53, 0xffff0000, v18
	v_lshl_add_u64 v[28:29], s[52:53], 0, v[28:29]
	v_pk_fma_f32 v[52:53], v[32:33], v[52:53], v[42:43] op_sel_hi:[0,1,1] neg_lo:[0,0,1] neg_hi:[0,0,1]
	v_cmp_gt_i32_e32 vcc, s36, v30
	v_lshlrev_b32_e32 v14, 16, v15
	v_and_b32_e32 v15, 0xffff0000, v15
	v_lshlrev_b32_e32 v18, 16, v19
	v_and_b32_e32 v19, 0xffff0000, v19
	v_cndmask_b32_e64 v0, 0, 1.0, vcc
	s_waitcnt vmcnt(7)
	v_lshlrev_b32_e32 v60, 16, v22
	v_and_b32_e32 v61, 0xffff0000, v22
	v_lshlrev_b32_e32 v22, 16, v23
	v_and_b32_e32 v23, 0xffff0000, v23
	v_pk_fma_f32 v[18:19], v[32:33], v[18:19], v[14:15] op_sel_hi:[0,1,1] neg_lo:[0,0,1] neg_hi:[0,0,1]
	v_ashrrev_i32_e32 v31, 31, v30
	s_movk_i32 s26, 0x17f
	v_cmp_lt_i32_e32 vcc, s26, v26
	s_waitcnt vmcnt(2)
	v_pk_fma_f32 v[38:39], v[38:39], v[52:53], v[42:43]
	v_pk_fma_f32 v[18:19], v[18:19], v[40:41], v[14:15]
	v_pk_fma_f32 v[14:15], v[0:1], v[22:23], v[14:15] op_sel_hi:[0,1,1] neg_lo:[0,0,1] neg_hi:[0,0,1]
	v_pk_fma_f32 v[28:29], v[0:1], v[60:61], v[42:43] op_sel_hi:[0,1,1] neg_lo:[0,0,1] neg_hi:[0,0,1]
	s_waitcnt vmcnt(0)
	v_pk_fma_f32 v[22:23], v[14:15], v[88:89], v[18:19]
	v_lshlrev_b32_e32 v14, 16, v16
	v_and_b32_e32 v15, 0xffff0000, v16
	v_lshlrev_b32_e32 v18, 16, v20
	v_and_b32_e32 v19, 0xffff0000, v20
	v_pk_fma_f32 v[28:29], v[86:87], v[28:29], v[38:39]
	v_lshlrev_b32_e32 v38, 16, v24
	v_and_b32_e32 v39, 0xffff0000, v24
	v_pk_fma_f32 v[18:19], v[32:33], v[18:19], v[14:15] op_sel_hi:[0,1,1] neg_lo:[0,0,1] neg_hi:[0,0,1]
	v_pk_fma_f32 v[18:19], v[18:19], v[34:35], v[14:15]
	v_pk_fma_f32 v[14:15], v[0:1], v[38:39], v[14:15] op_sel_hi:[0,1,1] neg_lo:[0,0,1] neg_hi:[0,0,1]
	v_pk_fma_f32 v[18:19], v[14:15], v[82:83], v[18:19]
	v_lshlrev_b32_e32 v14, 16, v17
	v_and_b32_e32 v15, 0xffff0000, v17
	v_lshlrev_b32_e32 v16, 16, v21
	v_and_b32_e32 v17, 0xffff0000, v21
	v_lshlrev_b32_e32 v20, 16, v25
	v_and_b32_e32 v21, 0xffff0000, v25
	v_pk_fma_f32 v[16:17], v[32:33], v[16:17], v[14:15] op_sel_hi:[0,1,1] neg_lo:[0,0,1] neg_hi:[0,0,1]
	v_pk_fma_f32 v[16:17], v[16:17], v[36:37], v[14:15]
	v_pk_fma_f32 v[14:15], v[0:1], v[20:21], v[14:15] op_sel_hi:[0,1,1] neg_lo:[0,0,1] neg_hi:[0,0,1]
	v_pk_fma_f32 v[16:17], v[14:15], v[84:85], v[16:17]
	v_lshl_add_u64 v[14:15], s[56:57], 0, v[30:31]
	s_and_saveexec_b64 s[26:27], vcc
	s_xor_b64 s[46:47], exec, s[26:27]
	s_cbranch_execz .LBB0_1005
	v_cmp_lt_u32_e32 vcc, s88, v26
	s_and_saveexec_b64 s[26:27], vcc
	s_xor_b64 s[58:59], exec, s[26:27]
	s_cbranch_execz .LBB0_1002
	s_movk_i32 s26, 0x47f
	v_cmp_lt_u32_e32 vcc, s26, v26
	s_and_saveexec_b64 s[26:27], vcc
	s_xor_b64 s[60:61], exec, s[26:27]
	s_cbranch_execz .LBB0_999
	s_movk_i32 s26, 0x4bf
	v_cmp_lt_u32_e32 vcc, s26, v26
	s_and_saveexec_b64 s[26:27], vcc
	s_xor_b64 s[26:27], exec, s[26:27]
	s_cbranch_execz .LBB0_996
	s_movk_i32 s28, 0x4ff
	v_cmp_lt_u32_e32 vcc, s28, v26
	s_and_saveexec_b64 s[28:29], vcc
	s_xor_b64 s[62:63], exec, s[28:29]
	s_cbranch_execz .LBB0_993
	v_mul_f32_e32 v18, 0xbfb8aa3b, v18
	v_mul_f32_e32 v19, 0xbfb8aa3b, v19
	v_mul_f32_e32 v16, 0xbfb8aa3b, v16
	v_mul_f32_e32 v0, 0xbfb8aa3b, v28
	v_mul_f32_e32 v20, 0xbfb8aa3b, v29
	v_mul_f32_e32 v21, 0xbfb8aa3b, v22
	v_mul_f32_e32 v22, 0xbfb8aa3b, v23
	v_exp_f32_e32 v18, v18
	v_exp_f32_e32 v19, v19
	v_exp_f32_e32 v16, v16
	v_mul_f32_e32 v17, 0xbfb8aa3b, v17
	v_exp_f32_e32 v0, v0
	v_exp_f32_e32 v20, v20
	v_exp_f32_e32 v21, v21
	v_exp_f32_e32 v22, v22
	v_exp_f32_e32 v17, v17
	v_add_f32_e32 v18, 1.0, v18
	v_add_f32_e32 v19, 1.0, v19
	v_add_f32_e32 v16, 1.0, v16
	v_lshlrev_b64 v[14:15], 9, v[14:15]
	v_add_f32_e32 v0, 1.0, v0
	v_add_f32_e32 v20, 1.0, v20
	v_add_f32_e32 v21, 1.0, v21
	v_add_f32_e32 v22, 1.0, v22
	v_rcp_f32_e32 v18, v18
	v_rcp_f32_e32 v19, v19
	v_rcp_f32_e32 v23, v16
	v_add_f32_e32 v16, 1.0, v17
	v_lshl_add_u64 v[14:15], s[14:15], 0, v[14:15]
	v_rcp_f32_e32 v0, v0
	v_rcp_f32_e32 v20, v20
	v_rcp_f32_e32 v21, v21
	v_rcp_f32_e32 v22, v22
	v_rcp_f32_e32 v24, v16
	v_cvt_pk_bf16_f32 v16, v0, v20
	v_cvt_pk_bf16_f32 v17, v21, v22
	v_cvt_pk_bf16_f32 v18, v18, v19
	v_cvt_pk_bf16_f32 v19, v23, v24
	v_lshl_add_u64 v[14:15], v[26:27], 1, v[14:15]
	global_store_dwordx4 v[14:15], v[16:19], off offset:-2304

.LBB0_1007:
	s_or_b64 exec, exec, s[24:25]
	v_cmp_gt_i32_e32 vcc, s39, v50
	s_and_saveexec_b64 s[24:25], vcc
	s_cbranch_execz .LBB0_888
	s_waitcnt vmcnt(4)
	v_mov_b32_e32 v14, v108
	v_mov_b32_e32 v21, v109
	s_waitcnt vmcnt(5)
	v_ashrrev_i32_e32 v15, 31, v14
	v_lshlrev_b64 v[16:17], 2, v[14:15]
	v_lshl_add_u64 v[26:27], s[50:51], 0, v[16:17]
	global_load_dwordx4 v[22:25], v[26:27], off offset:16
	s_nop 0
	global_load_dwordx4 v[26:29], v[26:27], off
	v_lshl_add_u64 v[102:103], s[52:53], 0, v[16:17]
	global_load_dwordx4 v[90:93], v[102:103], off offset:16
	global_load_dwordx4 v[94:97], v[102:103], off
	s_waitcnt vmcnt(8)
	v_add_u32_e32 v18, s13, v21
	v_cmp_lt_i32_e32 vcc, s30, v18
	s_waitcnt vmcnt(6)
	v_lshlrev_b32_e32 v38, 16, v2
	v_and_b32_e32 v39, 0xffff0000, v2
	v_cndmask_b32_e64 v20, 0, 1.0, vcc
	s_waitcnt vmcnt(5)
	v_lshlrev_b32_e32 v30, 16, v6
	v_and_b32_e32 v31, 0xffff0000, v6
	v_lshl_add_u64 v[16:17], s[52:53], 0, v[16:17]
	v_pk_fma_f32 v[30:31], v[20:21], v[30:31], v[38:39] op_sel_hi:[0,1,1] neg_lo:[0,0,1] neg_hi:[0,0,1]
	v_cmp_gt_i32_e32 vcc, s36, v18
	v_lshlrev_b32_e32 v2, 16, v3
	v_and_b32_e32 v3, 0xffff0000, v3
	v_lshlrev_b32_e32 v6, 16, v7
	v_and_b32_e32 v7, 0xffff0000, v7
	v_cndmask_b32_e64 v0, 0, 1.0, vcc
	s_waitcnt vmcnt(4)
	v_lshlrev_b32_e32 v40, 16, v10
	v_and_b32_e32 v41, 0xffff0000, v10
	v_lshlrev_b32_e32 v10, 16, v11
	v_and_b32_e32 v11, 0xffff0000, v11
	v_pk_fma_f32 v[6:7], v[20:21], v[6:7], v[2:3] op_sel_hi:[0,1,1] neg_lo:[0,0,1] neg_hi:[0,0,1]
	v_ashrrev_i32_e32 v19, 31, v18
	s_movk_i32 s26, 0x17f
	v_cmp_lt_i32_e32 vcc, s26, v14
	s_waitcnt vmcnt(2)
	v_pk_fma_f32 v[26:27], v[26:27], v[30:31], v[38:39]
	v_pk_fma_f32 v[6:7], v[6:7], v[28:29], v[2:3]
	v_pk_fma_f32 v[2:3], v[0:1], v[10:11], v[2:3] op_sel_hi:[0,1,1] neg_lo:[0,0,1] neg_hi:[0,0,1]
	v_pk_fma_f32 v[16:17], v[0:1], v[40:41], v[38:39] op_sel_hi:[0,1,1] neg_lo:[0,0,1] neg_hi:[0,0,1]
	s_waitcnt vmcnt(0)
	v_pk_fma_f32 v[10:11], v[2:3], v[96:97], v[6:7]
	v_lshlrev_b32_e32 v2, 16, v4
	v_and_b32_e32 v3, 0xffff0000, v4
	v_lshlrev_b32_e32 v6, 16, v8
	v_and_b32_e32 v7, 0xffff0000, v8
	v_pk_fma_f32 v[16:17], v[94:95], v[16:17], v[26:27]
	v_lshlrev_b32_e32 v26, 16, v12
	v_and_b32_e32 v27, 0xffff0000, v12
	v_pk_fma_f32 v[6:7], v[20:21], v[6:7], v[2:3] op_sel_hi:[0,1,1] neg_lo:[0,0,1] neg_hi:[0,0,1]
	v_pk_fma_f32 v[6:7], v[6:7], v[22:23], v[2:3]
	v_pk_fma_f32 v[2:3], v[0:1], v[26:27], v[2:3] op_sel_hi:[0,1,1] neg_lo:[0,0,1] neg_hi:[0,0,1]
	v_pk_fma_f32 v[6:7], v[2:3], v[90:91], v[6:7]
	v_lshlrev_b32_e32 v2, 16, v5
	v_and_b32_e32 v3, 0xffff0000, v5
	v_lshlrev_b32_e32 v4, 16, v9
	v_and_b32_e32 v5, 0xffff0000, v9
	v_lshlrev_b32_e32 v8, 16, v13
	v_and_b32_e32 v9, 0xffff0000, v13
	v_pk_fma_f32 v[4:5], v[20:21], v[4:5], v[2:3] op_sel_hi:[0,1,1] neg_lo:[0,0,1] neg_hi:[0,0,1]
	v_pk_fma_f32 v[4:5], v[4:5], v[24:25], v[2:3]
	v_pk_fma_f32 v[2:3], v[0:1], v[8:9], v[2:3] op_sel_hi:[0,1,1] neg_lo:[0,0,1] neg_hi:[0,0,1]
	v_pk_fma_f32 v[4:5], v[2:3], v[92:93], v[4:5]
	v_lshl_add_u64 v[2:3], s[56:57], 0, v[18:19]
	s_and_saveexec_b64 s[26:27], vcc
	s_xor_b64 s[44:45], exec, s[26:27]
	s_cbranch_execz .LBB0_1034
	v_cmp_lt_u32_e32 vcc, s88, v14
	s_and_saveexec_b64 s[26:27], vcc
	s_xor_b64 s[46:47], exec, s[26:27]
	s_cbranch_execz .LBB0_1031
	s_movk_i32 s26, 0x47f
	v_cmp_lt_u32_e32 vcc, s26, v14
	s_and_saveexec_b64 s[26:27], vcc
	s_xor_b64 s[58:59], exec, s[26:27]
	s_cbranch_execz .LBB0_1028
	s_movk_i32 s26, 0x4bf
	v_cmp_lt_u32_e32 vcc, s26, v14
	s_and_saveexec_b64 s[26:27], vcc
	s_xor_b64 s[26:27], exec, s[26:27]
	s_cbranch_execz .LBB0_1025
	s_movk_i32 s28, 0x4ff
	v_cmp_lt_u32_e32 vcc, s28, v14
	s_and_saveexec_b64 s[28:29], vcc
	s_xor_b64 s[60:61], exec, s[28:29]
	s_cbranch_execz .LBB0_1022
	v_mul_f32_e32 v6, 0xbfb8aa3b, v6
	v_mul_f32_e32 v7, 0xbfb8aa3b, v7
	v_mul_f32_e32 v4, 0xbfb8aa3b, v4
	v_mul_f32_e32 v0, 0xbfb8aa3b, v16
	v_mul_f32_e32 v8, 0xbfb8aa3b, v17
	v_mul_f32_e32 v9, 0xbfb8aa3b, v10
	v_mul_f32_e32 v10, 0xbfb8aa3b, v11
	v_exp_f32_e32 v6, v6
	v_exp_f32_e32 v7, v7
	v_exp_f32_e32 v4, v4
	v_mul_f32_e32 v5, 0xbfb8aa3b, v5
	v_exp_f32_e32 v0, v0
	v_exp_f32_e32 v8, v8
	v_exp_f32_e32 v9, v9
	v_exp_f32_e32 v10, v10
	v_exp_f32_e32 v5, v5
	v_add_f32_e32 v6, 1.0, v6
	v_add_f32_e32 v7, 1.0, v7
	v_add_f32_e32 v4, 1.0, v4
	v_lshlrev_b64 v[2:3], 9, v[2:3]
	v_add_f32_e32 v0, 1.0, v0
	v_add_f32_e32 v8, 1.0, v8
	v_add_f32_e32 v9, 1.0, v9
	v_add_f32_e32 v10, 1.0, v10
	v_rcp_f32_e32 v6, v6
	v_rcp_f32_e32 v7, v7
	v_rcp_f32_e32 v11, v4
	v_add_f32_e32 v4, 1.0, v5
	v_lshl_add_u64 v[2:3], s[14:15], 0, v[2:3]
	v_rcp_f32_e32 v0, v0
	v_rcp_f32_e32 v8, v8
	v_rcp_f32_e32 v9, v9
	v_rcp_f32_e32 v10, v10
	v_rcp_f32_e32 v12, v4
	v_cvt_pk_bf16_f32 v4, v0, v8
	v_cvt_pk_bf16_f32 v5, v9, v10
	v_cvt_pk_bf16_f32 v6, v6, v7
	v_cvt_pk_bf16_f32 v7, v11, v12
	v_lshl_add_u64 v[2:3], v[14:15], 1, v[2:3]
	global_store_dwordx4 v[2:3], v[4:7], off offset:-2304
